# attention meta tile: dead exp(-m) and the l += 0*exp(-m) fmac removed (adds exactly zero)
# baseline (speedup 1.0000x reference)
; DI void attn_item(const Params& p, unsigned char* lds, int b, int hd, int qb, float lam) {
;     ...
;     const int qs = qb * 128 + rt * 32 + l31;
;     const size_t grow = (size_t)b * 4096 + qs;
;     bf16x8 qf[4];
; #pragma unroll
;     for (int ks = 0; ks < 4; ++ks) qf[ks] = *(const bf16x8*)(aq + grow * 1024 + hd * 128 + sub * 64 + ks * 16 + 8 * h);
;     f32x16 O[4];
; #pragma unroll
;     for (int d = 0; d < 4; ++d)
; #pragma unroll
;         for (int i = 0; i < 16; ++i) O[d][i] = 0.f;
;     float m = 0.f, l = 0.f;
;     const int T = 2 * qb + 3;
;     u32x4 k0r[2], v0r[2];
;     const int krow_ = tid >> 4, kc_ = tid & 15, vdv_ = tid >> 3, vc_ = tid & 7;
;     const bf16_t* kp = ak + ((size_t)b * 4096 + krow_) * 1024 + hd * 128 + kc_ * 8;
;     const bf16_t* vp_ = avT + ((size_t)(b * 8 + hd) * 128 + vdv_) * 4096 + vc_ * 8;
;     ...
;     {
;         const bf16_t* km_ = akm + (size_t)krow_ * 1024 + hd * 128 + kc_ * 8;
;         k0r[0] = *(const u32x4*)km_; k0r[1] = *(const u32x4*)(km_ + 32 * 1024);
;         const bf16_t* vm_ = avTm + (size_t)(hd * 128 + vdv_) * 64 + vc_ * 8;
;         v0r[0] = *(const u32x4*)vm_; v0r[1] = *(const u32x4*)(vm_ + 64 * 64);
;     }
;     u32x4 k1r[2], v1r[2];
;     A_LOAD_REAL(k1r, v1r);
; #pragma unroll
;     for (int ks = 0; ks < 4; ++ks) asm volatile("" : "+v"(qf[ks]));
;     A_STORE(k0r, v0r, 0);
; DI void phase2(const Params& p, unsigned char* lds) {
;     ...
;         const unsigned x = item >> 16, idx = item & 0xffffu;
;         if (idx < N_GLA) { const unsigned gi = x * N_GLA + idx; gla_item<GLA_DL>(p, lds, gi / (4 * NSL), (gi / NSL) & 3, gi % NSL); }
;         else { const unsigned a = idx - N_GLA, pair = 4 * x + ((a >> 2) & 3); attn_item(p, lds, pair & 3, pair >> 2, 31 - (int)(((a >> 4) << 2) + (a & 3)), lam); }
.Lq_noclaim:
	s_add_i32 s4, s0, -8
	s_lshr_b32 s0, s4, 2
	s_and_b32 s0, s0, 0x3ffffffc
	s_and_b32 s5, s8, 3
	s_or_b32 s0, s0, s5
	v_mov_b32_e32 v132, v186
	s_sub_i32 s0, 31, s0
	s_lshl_b32 s6, s0, 7
	v_lshrrev_b32_e32 v1, 1, v132
	v_and_b32_e32 v146, 31, v132
	v_and_b32_e32 v148, 0x60, v1
	s_bfe_u32 s11, s4, 0x20002
	v_or3_b32 v138, v148, s6, v146
	s_lshl_b32 s54, s11, 12
	v_ashrrev_i32_e32 v139, 31, v138
	v_lshl_add_u64 v[2:3], v[138:139], 0, s[54:55]
	v_ashrrev_i32_e32 v147, 8, v132
	v_lshlrev_b64 v[136:137], 11, v[2:3]
	v_lshl_add_u64 v[2:3], s[68:69], 0, v[136:137]
	s_lshl_b32 s6, s9, 8
	s_mov_b32 s7, s55
	v_lshlrev_b32_e32 v4, 6, v147
	v_lshl_add_u64 v[2:3], v[2:3], 0, s[6:7]
	v_ashrrev_i32_e32 v5, 31, v4
	v_lshl_add_u64 v[2:3], v[4:5], 1, v[2:3]
	v_ashrrev_i32_e32 v4, 4, v132
	v_ashrrev_i32_e32 v5, 31, v4
	v_lshlrev_b64 v[12:13], 11, v[4:5]
	v_bfe_u32 v149, v132, 5, 1
	v_lshlrev_b32_e32 v1, 4, v132
	v_lshl_add_u64 v[12:13], s[64:65], 0, v[12:13]
	v_lshlrev_b32_e32 v98, 4, v149
	v_and_b32_e32 v140, 0xf0, v1
	v_mov_b32_e32 v141, v99
	v_lshl_add_u64 v[12:13], v[12:13], 0, s[6:7]
	v_lshl_add_u64 v[2:3], v[2:3], 0, v[98:99]
	v_lshl_add_u64 v[12:13], v[12:13], 0, v[140:141]
	global_load_dwordx4 v[100:103], v[2:3], off
	global_load_dwordx4 v[104:107], v[2:3], off offset:32
	global_load_dwordx4 v[108:111], v[2:3], off offset:64
	global_load_dwordx4 v[112:115], v[2:3], off offset:96
	global_load_dwordx4 v[116:119], v[12:13], off
	v_add_co_u32_e32 v2, vcc, s43, v12
	s_lshl_b32 s10, s9, 7
	v_ashrrev_i32_e32 v6, 3, v132
	v_addc_co_u32_e32 v3, vcc, 0, v13, vcc
	global_load_dwordx4 v[120:123], v[2:3], off
	v_add_u32_e32 v2, s10, v6
	v_ashrrev_i32_e32 v3, 31, v2
	v_lshlrev_b64 v[2:3], 7, v[2:3]
	v_and_b32_e32 v10, 0x70, v1
	v_mov_b32_e32 v11, v99
	v_lshl_add_u64 v[2:3], s[62:63], 0, v[2:3]
	v_lshl_add_u64 v[2:3], v[2:3], 0, v[10:11]
	global_load_dwordx4 v[124:127], v[2:3], off
	v_lshl_add_u64 v[8:9], v[4:5], 0, s[54:55]
	v_lshlrev_b64 v[8:9], 11, v[8:9]
	v_add_co_u32_e32 v2, vcc, s56, v2
	v_lshl_add_u64 v[8:9], s[44:45], 0, v[8:9]
	s_lshl_b32 s11, s11, 10
	v_addc_co_u32_e32 v3, vcc, 0, v3, vcc
	v_lshl_add_u64 v[8:9], v[8:9], 0, s[6:7]
	s_add_i32 s54, s11, s10
	v_ashrrev_i32_e32 v7, 31, v6
	global_load_dwordx4 v[128:131], v[2:3], off
	v_lshl_add_u64 v[82:83], v[8:9], 0, v[140:141]
	v_lshl_add_u64 v[8:9], v[6:7], 0, s[54:55]
	v_lshlrev_b64 v[8:9], 13, v[8:9]
	v_lshl_add_u64 v[8:9], s[60:61], 0, v[8:9]
	v_add_co_u32_e32 v2, vcc, s43, v82
	v_lshl_add_u64 v[84:85], v[8:9], 0, v[10:11]
	s_nop 0
	v_addc_co_u32_e32 v3, vcc, 0, v83, vcc
	v_add_co_u32_e32 v8, vcc, s74, v84
	global_load_dwordx4 v[74:77], v[82:83], off
	global_load_dwordx4 v[70:73], v[84:85], off
	v_addc_co_u32_e32 v9, vcc, 0, v85, vcc
	global_load_dwordx4 v[78:81], v[2:3], off
	global_load_dwordx4 v[66:69], v[8:9], off
	v_lshlrev_b32_e32 v2, 3, v132
	v_mul_lo_u32 v139, v4, s75
	v_add_u32_e32 v4, 0x200, v132
	v_and_b32_e32 v150, 0x60, v1
	v_and_b32_e32 v151, 8, v2
	v_lshrrev_b32_e32 v5, 4, v4
	v_add3_u32 v1, 0, v150, v151
	v_mul_lo_u32 v152, v6, s52
	v_add_u32_e32 v3, 0, v140
	v_mul_lo_u32 v141, v5, s75
	v_add_u32_e32 v97, v1, v152
	v_add_u32_e32 v87, v3, v139
	v_add_u32_e32 v96, v3, v141
	v_add_u32_e32 v2, 0x4000, v97
	s_waitcnt vmcnt(11)
	s_waitcnt vmcnt(10)
	s_waitcnt vmcnt(9)
	s_waitcnt vmcnt(8)
	s_waitcnt vmcnt(7)
	ds_write_b128 v87, v[116:119]
	v_mad_u32_u24 v42, v146, s75, 0
	v_lshl_or_b32 v154, v147, 7, v98
	s_waitcnt vmcnt(6)
	ds_write_b128 v96, v[120:123]
	s_waitcnt vmcnt(5)
	ds_write2_b64 v2, v[124:125], v[126:127] offset0:128 offset1:130
	v_lshrrev_b32_e32 v2, 3, v4
	v_mul_lo_u32 v153, v2, s52
	v_add_u32_e32 v155, v1, v153
	v_add_u32_e32 v1, 0x4000, v155
	s_waitcnt vmcnt(4)
	ds_write2_b64 v1, v[128:129], v[130:131] offset0:128 offset1:130
	v_add_u32_e32 v1, v42, v154
	s_waitcnt lgkmcnt(0)
	s_barrier
; DI void attn_s(const unsigned char* sK, int tt, int qb, int qs, int sub, int l31, int h,
;                const bf16x8 (&qf)[4], f32x16 (&O)[4], float& m, float& l, bf16x8 (&pb)[4]) {
;     ...
;     if (tt == 0 || __builtin_amdgcn_ballot_w64(mx > 8.0f) != 0ull) {
;         const float delta = tt == 0 ? mx : fmaxf(mx, 0.f);
;         const float alpha = __builtin_amdgcn_exp2f(-delta);
;         m += delta;
;         l *= alpha;
; #pragma unroll
;         for (int d = 0; d < 4; ++d) O[d] = O[d] * alpha;
; #pragma unroll
;         for (int k2 = 0; k2 < 2; ++k2) st[k2] = st[k2] - delta;
;     }
; #pragma unroll
;     for (int k2 = 0; k2 < 2; ++k2)
; #pragma unroll
;         for (int i = 0; i < 16; ++i) st[k2][i] = __builtin_amdgcn_exp2f(st[k2][i]);
;     {
;         const f32x16 sv = st[0] + st[1];
;         const float ps = (((sv[0] + sv[1]) + (sv[2] + sv[3])) + ((sv[4] + sv[5]) + (sv[6] + sv[7]))) + (((sv[8] + sv[9]) + (sv[10] + sv[11])) + ((sv[12] + sv[13]) + (sv[14] + sv[15])));
;         l += ps;
;     }
	ds_read_b128 v[26:29], v1 offset:8704
	ds_read_b128 v[30:33], v1 offset:8736
	ds_read_b128 v[34:37], v1 offset:8768
	ds_read_b128 v[38:41], v1 offset:8800
	v_mov_b32_e32 v10, v0
	v_mov_b32_e32 v11, v0
	v_mov_b32_e32 v12, v0
	v_mov_b32_e32 v13, v0
	v_mov_b32_e32 v14, v0
	v_mov_b32_e32 v15, v0
	v_mov_b32_e32 v1, v0
	v_mov_b32_e32 v2, v0
	v_mov_b32_e32 v3, v0
	v_mov_b32_e32 v4, v0
	v_mov_b32_e32 v5, v0
	v_mov_b32_e32 v6, v0
	v_mov_b32_e32 v7, v0
	v_mov_b32_e32 v8, v0
	v_mov_b32_e32 v9, v0
	v_mov_b64_e32 v[24:25], v[14:15]
	v_mov_b64_e32 v[22:23], v[12:13]
	v_mov_b64_e32 v[20:21], v[10:11]
	v_mov_b64_e32 v[18:19], v[8:9]
	v_mov_b64_e32 v[16:17], v[6:7]
	v_mov_b64_e32 v[14:15], v[4:5]
	v_mov_b64_e32 v[12:13], v[2:3]
	v_mov_b64_e32 v[10:11], v[0:1]
	s_waitcnt lgkmcnt(3)
	s_nop 0
	v_mfma_f32_32x32x16_bf16 v[10:25], v[26:29], v[100:103], v[10:25]
	s_waitcnt lgkmcnt(2)
	v_mfma_f32_32x32x16_bf16 v[10:25], v[30:33], v[104:107], v[10:25]
	s_waitcnt lgkmcnt(1)
	v_mfma_f32_32x32x16_bf16 v[10:25], v[34:37], v[108:111], v[10:25]
	v_max3_f32 v1, v188, v188, v188
	s_nop 0
	v_max3_f32 v2, v1, v1, v1
	s_waitcnt lgkmcnt(0)
	v_mfma_f32_32x32x16_bf16 v[10:25], v[38:41], v[112:115], v[10:25]
	v_max3_f32 v3, v188, v188, v18
	v_max3_f32 v4, v19, v20, v21
	v_max3_f32 v5, v22, v23, v24
	s_nop 0
	v_max3_f32 v1, v1, v3, v4
	s_nop 10
	v_max_f32_e32 v6, v25, v25
	v_max3_f32 v1, v2, v2, v1
	v_max_f32_e32 v6, 0xff800000, v6
	v_max3_f32 v1, v1, v5, v6
	s_nop 0
	v_mov_b32_e32 v2, v1
	s_nop 1
	v_permlane32_swap_b32_e32 v1, v2
	v_max_f32_e32 v2, v2, v2
	v_max_f32_e32 v1, v1, v1
	v_max_f32_e32 v86, v1, v2
	v_sub_f32_e32 v1, 0xff800000, v86
	v_sub_f32_e32 v19, v19, v86
	v_sub_f32_e32 v26, v18, v86
	v_sub_f32_e32 v21, v21, v86
	v_sub_f32_e32 v20, v20, v86
	v_exp_f32_e32 v18, v1
	v_exp_f32_e32 v26, v26
	v_exp_f32_e32 v27, v19
	v_sub_f32_e32 v23, v23, v86
	v_sub_f32_e32 v22, v22, v86
	v_exp_f32_e32 v28, v20
	v_exp_f32_e32 v29, v21
	v_sub_f32_e32 v25, v25, v86
	v_sub_f32_e32 v24, v24, v86
	v_exp_f32_e32 v30, v22
	v_exp_f32_e32 v31, v23
	v_exp_f32_e32 v32, v24
	v_exp_f32_e32 v33, v25
	v_pk_add_f32 v[34:35], v[18:19], v[26:27] op_sel_hi:[0,1]
	v_add_f32_e32 v36, v18, v18
	v_pk_add_f32 v[24:25], v[18:19], v[28:29] op_sel_hi:[0,1]
	v_mov_b32_e32 v37, v34
	v_mov_b32_e32 v34, v36
	v_pk_add_f32 v[22:23], v[18:19], v[30:31] op_sel_hi:[0,1]
	v_pk_add_f32 v[34:35], v[36:37], v[34:35]
	v_mov_b32_e32 v37, v24
	v_mov_b32_e32 v24, v36
	v_pk_add_f32 v[20:21], v[18:19], v[32:33] op_sel_hi:[0,1]
	v_pk_add_f32 v[24:25], v[36:37], v[24:25]
	v_mov_b32_e32 v37, v22
	v_mov_b32_e32 v22, v36
	v_pk_add_f32 v[22:23], v[36:37], v[22:23]
	v_mov_b32_e32 v37, v20
	v_mov_b32_e32 v20, v36
	v_pk_add_f32 v[20:21], v[36:37], v[20:21]
	v_cvt_pk_bf16_f32 v88, v18, v18
	v_lshlrev_b32_e32 v18, 7, v146
	v_pk_add_f32 v[24:25], v[34:35], v[24:25]
	v_pk_add_f32 v[20:21], v[22:23], v[20:21]
	v_sub_u32_e32 v18, v42, v18
	v_pk_add_f32 v[20:21], v[24:25], v[20:21]
	v_add_u32_e32 v185, v18, v98
	v_add_f32_e32 v1, v20, v21
	ds_read_b128 v[160:163], v185 offset:17504
	ds_read_b128 v[164:167], v185 offset:22112
	ds_read_b128 v[168:171], v185 offset:26720
	ds_read_b128 v[172:175], v185 offset:31328
	v_mov_b32_e32 v89, v88
	v_mov_b32_e32 v90, v88
	v_mov_b32_e32 v91, v88
	v_cvt_pk_bf16_f32 v156, v26, v27
	v_cvt_pk_bf16_f32 v157, v28, v29
	v_cvt_pk_bf16_f32 v158, v30, v31
	v_cvt_pk_bf16_f32 v159, v32, v33
	s_waitcnt lgkmcnt(3)
	v_mfma_f32_32x32x16_bf16 v[50:65], v[160:163], v[156:159], 0
	s_waitcnt vmcnt(3)
	ds_write_b128 v87, v[74:77] offset:35840
	s_waitcnt vmcnt(1)
	ds_write_b128 v96, v[78:81] offset:35840
	v_add_u32_e32 v74, 0xd000, v97
	ds_write2_b64 v74, v[70:71], v[72:73] offset1:2
	v_add_u32_e32 v70, 0xd000, v155
	s_cmpk_gt_u32 s4, 0x7f
	s_waitcnt vmcnt(0)
	ds_write2_b64 v70, v[66:67], v[68:69] offset1:2
	v_readfirstlane_b32 s99, v238
	s_nop 3
	v_writelane_b32 v236, s99, 63
	s_waitcnt lgkmcnt(6)
	v_mfma_f32_32x32x16_bf16 v[34:49], v[164:167], v[156:159], 0
	s_waitcnt lgkmcnt(0)
	s_barrier
	v_mfma_f32_32x32x16_bf16 v[18:33], v[168:171], v[156:159], 0
	v_mfma_f32_32x32x16_bf16 v[2:17], v[172:175], v[156:159], 0
	s_cbranch_scc1 .LBB0_1824
	s_lshr_b32 s4, s4, 1
	s_lshl_b32 s5, s5, 1
	s_and_b32 s4, s4, 0x7ffffff8
	s_lshl_b32 s0, s0, 1
	s_or_b32 s4, s5, s4
	v_mul_u32_u24_e32 v155, 0x110, v146
	v_mul_u32_u24_e32 v156, 0x90, v146
	s_mov_b32 s13, 1
	s_add_i32 s6, s0, 3
	v_lshl_add_u64 v[142:143], v[84:85], 0, s[88:89]
	v_lshl_add_u64 v[142:143], v[142:143], 0, s[88:89]
	v_add_f32_e32 v157, 0, v86
	v_lshl_add_u64 v[144:145], v[82:83], 0, s[90:91]
	v_lshl_add_u64 v[144:145], v[144:145], 0, s[90:91]
	s_mov_b32 s7, 2
	v_lshl_or_b32 v158, v149, 2, 59
	s_sub_i32 s11, 0, s4
	s_movk_i32 s12, 0xffc0
	v_xor_b32_e32 v240, 0x80000000, v157
	v_mov_b32_e32 v241, v240
	v_mov_b32_e32 v242, v240
	v_mov_b32_e32 v243, v240
	v_mov_b32_e32 v244, v240
	v_mov_b32_e32 v245, v240
	v_mov_b32_e32 v246, v240
	v_mov_b32_e32 v247, v240
	v_mov_b32_e32 v248, v240
	v_mov_b32_e32 v249, v240
	v_mov_b32_e32 v250, v240
	v_mov_b32_e32 v251, v240
	v_mov_b32_e32 v252, v240
	v_mov_b32_e32 v253, v240
	v_mov_b32_e32 v254, v240
	v_mov_b32_e32 v255, v240
	v_readfirstlane_b32 s99, v147
	s_cmp_eq_u32 s99, 1
	s_cbranch_scc0 .Lpipe_nooffs
	s_barrier
